# attention piece prologue: the 8 Q-fragment loads issued before waiting for the kmean load (one exposed round trip less per piece)
# baseline (speedup 1.0000x reference)
; #define LAS __attribute__((address_space(3)))
; __device__ __forceinline__ void phase_moba_attn(const Params& P, LAS unsigned char* lds, int l, int qslot) {
;     ...
;         const unsigned x = y < 128u ? 896u + y : y - 128u;
;         if (tid == 0) nextx = __hip_atomic_fetch_add(qctr, 1u, __ATOMIC_RELAXED, __HIP_MEMORY_SCOPE_AGENT);
;         if (x >= 384u) {
;             if (x < 896u) sgu_item(P, lds, l, (int)(x - 384u));
;             else { const int tile = (int)(x - 896u) * 8 + wave; if (tile < 512) pool_tile(P, l, tile, lane); else conv_tile(P, l, tile - 512, lane); }
;             continue;
;         }
;         const int bh = (int)(x & 15u), rr = (int)(x >> 4);
;         const unsigned ent = (unsigned)((rr < 12 ? (TA >> (5 * rr)) : (TB >> (5 * (rr - 12)))) & 31ull);
;         const int i = (int)(ent & 15u), sp = (int)(ent >> 4);
;         int jlo = 0, jhi = i;
;         if (i >= 8) { const int h1 = (i + 1) >> 1; if (sp == 0) jhi = h1 - 1; else jlo = h1; }
;         const int nch = 4 * (jhi - jlo + 1);
;         const int t0 = 256 * i, tq = t0 + 32 * wave + ln, tql = 32 * wave + ln;
;         { const f32x4 v = *(const f32x4*)(kmean + (size_t)bh * NBLK * HD + 4 * tid); *(LAS f32x4*)(km + 4 * tid) = v; }
;         f16x8 qf[8];
;         { const f16* qrow = Q16 + ((size_t)bh * SEQ + tq) * HD + 8 * hf;
; #pragma unroll
;             for (int st = 0; st < 8; ++st) qf[st] = *(const f16x8*)(qrow + 16 * st); }
;         __syncthreads();
;         unsigned mask = 0u;
;         if (i <= 3) mask = (1u << i) - 1u;
;         else {
;             float v0 = -INFINITY, v1 = -INFINITY, v2 = -INFINITY; int i0 = 0, i1 = 0, i2 = 0;
.LBB0_893:
	s_or_b64 exec, exec, s[0:1]
	s_cmpk_lt_u32 s2, 0x80
	s_movk_i32 s0, 0x380
	s_cselect_b32 s63, s0, 0xffffff80
	s_add_i32 s63, s63, s2
	s_cmpk_lt_u32 s63, 0x180
	s_mov_b64 s[0:1], -1
	s_cbranch_scc0 .LBB0_925
	v_mov_b32_e32 v245, 0x14000
	v_lshl_add_u32 v245, v0, 2, v245
	ds_write_b32 v245, v192 offset:0
	ds_write_b32 v245, v193 offset:2048
	ds_write_b32 v245, v194 offset:4096
	ds_write_b32 v245, v195 offset:6144
	ds_write_b32 v245, v196 offset:8192
	ds_write_b32 v245, v197 offset:10240
	ds_write_b32 v245, v198 offset:12288
	ds_write_b32 v245, v199 offset:14336
	ds_write_b32 v245, v200 offset:16384
	ds_write_b32 v245, v201 offset:18432
	ds_write_b32 v245, v202 offset:20480
	ds_write_b32 v245, v203 offset:22528
	ds_write_b32 v245, v204 offset:24576
	ds_write_b32 v245, v205 offset:26624
	ds_write_b32 v245, v206 offset:28672
	s_waitcnt lgkmcnt(0)
	s_and_b32 s19, s2, 15
	s_lshr_b32 s2, s63, 4
	s_cmpk_lt_u32 s63, 0xc0
	s_mul_i32 s2, s2, 5
	s_cselect_b64 s[0:1], -1, 0
	s_sub_i32 s3, s2, 60
	s_and_b64 s[0:1], s[0:1], exec
	s_mov_b32 s0, 0xdad86e7
	s_cselect_b32 s1, s0, 0x44341
	s_mov_b32 s0, 0x5ae3fbef
	s_cselect_b32 s2, s2, s3
	s_cselect_b32 s0, s0, 0x3194a8ba
	s_lshl_b32 s56, s19, 13
	v_lshl_add_u64 v[4:5], v[162:163], 0, s[56:57]
	global_load_dwordx4 v[4:7], v[4:5], off
	s_lshr_b64 s[8:9], s[0:1], s2
	s_and_b32 s3, s8, 15
	s_lshl_b32 s2, s3, 8
	v_add_u32_e32 v8, s2, v219
	s_lshl_b32 s0, s19, 12
	s_mov_b32 s1, s57
	v_ashrrev_i32_e32 v9, 31, v8
	v_lshl_add_u64 v[214:215], s[0:1], 0, v[8:9]
	s_mov_b64 s[12:13], -1
	s_cmp_lt_u32 s3, 4
	v_lshlrev_b64 v[8:9], 8, v[214:215]
	v_lshl_add_u64 v[8:9], v[166:167], 0, v[8:9]
	global_load_dwordx4 v[98:101], v[8:9], off
	global_load_dwordx4 v[102:105], v[8:9], off offset:32
	global_load_dwordx4 v[106:109], v[8:9], off offset:64
	global_load_dwordx4 v[110:113], v[8:9], off offset:96
	global_load_dwordx4 v[114:117], v[8:9], off offset:128
	global_load_dwordx4 v[118:121], v[8:9], off offset:160
	global_load_dwordx4 v[122:125], v[8:9], off offset:192
	global_load_dwordx4 v[126:129], v[8:9], off offset:224
	s_waitcnt vmcnt(8)
	ds_write_b128 v220, v[4:7]
	s_waitcnt lgkmcnt(0)
	s_barrier
	s_cbranch_scc1 .LBB0_905
	v_and_b32_e32 v4, 64, v238
	v_xor_b32_e32 v2, 32, v238
	v_add_u32_e32 v4, 64, v4
	v_cmp_lt_i32_e32 vcc, v2, v4
	s_waitcnt vmcnt(7)
	v_cvt_f32_f16_e32 v4, v98
	v_cvt_f32_f16_sdwa v5, v98 dst_sel:DWORD dst_unused:UNUSED_PAD src0_sel:WORD_1
	v_cvt_f32_f16_e32 v6, v99
	v_cvt_f32_f16_sdwa v7, v99 dst_sel:DWORD dst_unused:UNUSED_PAD src0_sel:WORD_1
	v_cvt_f32_f16_e32 v8, v100
	v_cvt_f32_f16_sdwa v9, v100 dst_sel:DWORD dst_unused:UNUSED_PAD src0_sel:WORD_1
	v_cvt_f32_f16_e32 v10, v101
	v_cvt_f32_f16_sdwa v11, v101 dst_sel:DWORD dst_unused:UNUSED_PAD src0_sel:WORD_1
	s_waitcnt vmcnt(6)
	v_cvt_f32_f16_e32 v12, v102
	v_cvt_f32_f16_sdwa v13, v102 dst_sel:DWORD dst_unused:UNUSED_PAD src0_sel:WORD_1
	v_cvt_f32_f16_e32 v14, v103
	v_cvt_f32_f16_sdwa v15, v103 dst_sel:DWORD dst_unused:UNUSED_PAD src0_sel:WORD_1
	v_cvt_f32_f16_e32 v16, v104
	v_cvt_f32_f16_sdwa v17, v104 dst_sel:DWORD dst_unused:UNUSED_PAD src0_sel:WORD_1
	v_cvt_f32_f16_e32 v18, v105
	v_cvt_f32_f16_sdwa v19, v105 dst_sel:DWORD dst_unused:UNUSED_PAD src0_sel:WORD_1
	s_waitcnt vmcnt(5)
	v_cvt_f32_f16_e32 v20, v106
	v_cvt_f32_f16_sdwa v21, v106 dst_sel:DWORD dst_unused:UNUSED_PAD src0_sel:WORD_1
	v_cvt_f32_f16_e32 v22, v107
	v_cvt_f32_f16_sdwa v23, v107 dst_sel:DWORD dst_unused:UNUSED_PAD src0_sel:WORD_1
	v_cvt_f32_f16_e32 v24, v108
	v_cvt_f32_f16_sdwa v25, v108 dst_sel:DWORD dst_unused:UNUSED_PAD src0_sel:WORD_1
	v_cvt_f32_f16_e32 v26, v109
	v_cvt_f32_f16_sdwa v27, v109 dst_sel:DWORD dst_unused:UNUSED_PAD src0_sel:WORD_1
	s_waitcnt vmcnt(4)
	v_cvt_f32_f16_e32 v28, v110
	v_cvt_f32_f16_sdwa v29, v110 dst_sel:DWORD dst_unused:UNUSED_PAD src0_sel:WORD_1
	v_cvt_f32_f16_e32 v30, v111
	v_cvt_f32_f16_sdwa v31, v111 dst_sel:DWORD dst_unused:UNUSED_PAD src0_sel:WORD_1
	v_cvt_f32_f16_e32 v32, v112
	v_cvt_f32_f16_sdwa v33, v112 dst_sel:DWORD dst_unused:UNUSED_PAD src0_sel:WORD_1
	v_cvt_f32_f16_e32 v34, v113
	v_cvt_f32_f16_sdwa v35, v113 dst_sel:DWORD dst_unused:UNUSED_PAD src0_sel:WORD_1
	s_waitcnt vmcnt(3)
	v_cvt_f32_f16_e32 v36, v114
	v_cvt_f32_f16_sdwa v37, v114 dst_sel:DWORD dst_unused:UNUSED_PAD src0_sel:WORD_1
	v_cvt_f32_f16_e32 v38, v115
	v_cvt_f32_f16_sdwa v39, v115 dst_sel:DWORD dst_unused:UNUSED_PAD src0_sel:WORD_1
	v_cvt_f32_f16_e32 v40, v116
	v_cvt_f32_f16_sdwa v41, v116 dst_sel:DWORD dst_unused:UNUSED_PAD src0_sel:WORD_1
	v_cvt_f32_f16_e32 v42, v117
	v_cvt_f32_f16_sdwa v43, v117 dst_sel:DWORD dst_unused:UNUSED_PAD src0_sel:WORD_1
	s_waitcnt vmcnt(2)
	v_cvt_f32_f16_e32 v44, v118
	v_cvt_f32_f16_sdwa v45, v118 dst_sel:DWORD dst_unused:UNUSED_PAD src0_sel:WORD_1
	v_cvt_f32_f16_e32 v46, v119
	v_cvt_f32_f16_sdwa v47, v119 dst_sel:DWORD dst_unused:UNUSED_PAD src0_sel:WORD_1
	v_cvt_f32_f16_e32 v48, v120
	v_cvt_f32_f16_sdwa v49, v120 dst_sel:DWORD dst_unused:UNUSED_PAD src0_sel:WORD_1
	v_cvt_f32_f16_e32 v50, v121
	v_cvt_f32_f16_sdwa v51, v121 dst_sel:DWORD dst_unused:UNUSED_PAD src0_sel:WORD_1
	s_waitcnt vmcnt(1)
	v_cvt_f32_f16_e32 v52, v122
	v_cvt_f32_f16_sdwa v53, v122 dst_sel:DWORD dst_unused:UNUSED_PAD src0_sel:WORD_1
	v_cvt_f32_f16_e32 v54, v123
	v_cvt_f32_f16_sdwa v55, v123 dst_sel:DWORD dst_unused:UNUSED_PAD src0_sel:WORD_1
	v_cvt_f32_f16_e32 v56, v124
	v_cvt_f32_f16_sdwa v57, v124 dst_sel:DWORD dst_unused:UNUSED_PAD src0_sel:WORD_1
	v_cvt_f32_f16_e32 v58, v125
	v_cvt_f32_f16_sdwa v59, v125 dst_sel:DWORD dst_unused:UNUSED_PAD src0_sel:WORD_1
	s_waitcnt vmcnt(0)
	v_cvt_f32_f16_e32 v60, v126
	v_cvt_f32_f16_sdwa v61, v126 dst_sel:DWORD dst_unused:UNUSED_PAD src0_sel:WORD_1
	v_cvt_f32_f16_e32 v62, v127
	v_cvt_f32_f16_sdwa v63, v127 dst_sel:DWORD dst_unused:UNUSED_PAD src0_sel:WORD_1
	v_cvt_f32_f16_e32 v64, v128
	v_cvt_f32_f16_sdwa v65, v128 dst_sel:DWORD dst_unused:UNUSED_PAD src0_sel:WORD_1
	v_cvt_f32_f16_e32 v66, v129
	v_cvt_f32_f16_sdwa v67, v129 dst_sel:DWORD dst_unused:UNUSED_PAD src0_sel:WORD_1
	v_cndmask_b32_e32 v2, v238, v2, vcc
	s_mov_b32 s1, 0
	v_lshlrev_b32_e32 v2, 2, v2
	s_lshl_b32 s9, s3, 9
	v_mov_b32_e32 v69, 0xff800000
	v_mov_b32_e32 v71, 0
	v_mov_b32_e32 v68, 0
	v_mov_b32_e32 v72, 0
	v_mov_b32_e32 v70, 0xff800000
	v_mov_b32_e32 v73, 0xff800000
	s_mov_b32 s18, 0
